# permlane-swap reductions in all three residual epilogues, FFN-out residual loads issued as one burst of 16 again (k46 load order)
# speedup vs baseline: 1.0020x; 1.0020x over previous
.LBB0_274:
	v_mbcnt_lo_u32_b32 v94, -1, 0
	v_mbcnt_hi_u32_b32 v94, -1, v94
	s_lshl_b32 s9, s25, 8
	v_ashrrev_i32_e32 v95, 1, v94
	s_lshl_b32 s7, s26, 8
	s_or_b32 s9, s9, s59
	v_and_b32_e32 v95, -8, v95
	s_add_i32 s7, s7, s58
	v_add_u32_e32 v204, s9, v95
	v_ashrrev_i32_e32 v205, 31, v204
	v_and_or_b32 v234, v94, 15, s7
	v_lshlrev_b64 v[236:237], 1, v[204:205]
	v_ashrrev_i32_e32 v235, 31, v234
	v_lshlrev_b32_e32 v244, 2, v94
	v_cmp_gt_u32_e32 vcc, 16, v94
	v_lshl_add_u64 v[94:95], s[42:43], 0, v[236:237]
	v_lshlrev_b64 v[238:239], 11, v[234:235]
	v_lshl_add_u64 v[96:97], v[94:95], 0, v[238:239]
	global_load_dwordx4 v[190:193], v[96:97], off
	global_load_dwordx4 v[186:189], v[96:97], off offset:256
	v_or_b32_e32 v230, 16, v234
	v_ashrrev_i32_e32 v231, 31, v230
	v_or_b32_e32 v210, 32, v234
	v_lshlrev_b64 v[232:233], 11, v[230:231]
	v_ashrrev_i32_e32 v211, 31, v210
	v_or_b32_e32 v226, 48, v234
	v_lshl_add_u64 v[96:97], v[94:95], 0, v[232:233]
	v_lshlrev_b64 v[212:213], 11, v[210:211]
	v_ashrrev_i32_e32 v227, 31, v226
	v_add_u32_e32 v222, 0x80, v234
	global_load_dwordx4 v[182:185], v[96:97], off
	global_load_dwordx4 v[178:181], v[96:97], off offset:256
	v_lshl_add_u64 v[96:97], v[94:95], 0, v[212:213]
	v_lshlrev_b64 v[228:229], 11, v[226:227]
	v_ashrrev_i32_e32 v223, 31, v222
	v_add_u32_e32 v218, 0x90, v234
	global_load_dwordx4 v[174:177], v[96:97], off
	global_load_dwordx4 v[170:173], v[96:97], off offset:256
	v_lshl_add_u64 v[96:97], v[94:95], 0, v[228:229]
	v_lshlrev_b64 v[224:225], 11, v[222:223]
	v_ashrrev_i32_e32 v219, 31, v218
	v_add_u32_e32 v214, 0xa0, v234
	v_add_u32_e32 v206, 0xb0, v234
	global_load_dwordx4 v[166:169], v[96:97], off
	global_load_dwordx4 v[162:165], v[96:97], off offset:256
	v_lshl_add_u64 v[96:97], v[94:95], 0, v[224:225]
	v_lshlrev_b64 v[220:221], 11, v[218:219]
	v_ashrrev_i32_e32 v215, 31, v214
	v_ashrrev_i32_e32 v207, 31, v206
	global_load_dwordx4 v[158:161], v[96:97], off
	global_load_dwordx4 v[150:153], v[96:97], off offset:256
	v_lshl_add_u64 v[96:97], v[94:95], 0, v[220:221]
	v_lshlrev_b64 v[216:217], 11, v[214:215]
	v_lshlrev_b64 v[208:209], 11, v[206:207]
	global_load_dwordx4 v[142:145], v[96:97], off
	global_load_dwordx4 v[138:141], v[96:97], off offset:256
	v_lshl_add_u64 v[96:97], v[94:95], 0, v[216:217]
	v_lshl_add_u64 v[94:95], v[94:95], 0, v[208:209]
	global_load_dwordx4 v[126:129], v[96:97], off
	global_load_dwordx4 v[114:117], v[96:97], off offset:256
	global_load_dwordx4 v[106:109], v[94:95], off
	s_nop 0
	global_load_dwordx4 v[94:97], v[94:95], off offset:256
	v_xor_b32_e32 v245, 64, v244
	v_xor_b32_e32 v244, 0x80, v244
	s_lshl_b32 s82, s25, 2
	s_ashr_i32 s83, s82, 31
	s_waitcnt vmcnt(15)
	v_lshlrev_b32_e32 v246, 16, v190
	v_and_b32_e32 v247, 0xffff0000, v190
	v_lshlrev_b32_e32 v190, 16, v191
	v_and_b32_e32 v191, 0xffff0000, v191
	v_pk_fma_f32 v[156:157], v[156:157], 0.5, v[190:191] op_sel_hi:[1,0,1]
	v_lshlrev_b32_e32 v190, 16, v192
	v_and_b32_e32 v191, 0xffff0000, v192
	v_pk_fma_f32 v[146:147], v[146:147], 0.5, v[190:191] op_sel_hi:[1,0,1]
	v_pk_fma_f32 v[154:155], v[154:155], 0.5, v[246:247] op_sel_hi:[1,0,1]
	v_pk_add_f32 v[190:191], v[146:147], 0 op_sel_hi:[1,0]
	v_lshlrev_b32_e32 v146, 16, v193
	v_and_b32_e32 v147, 0xffff0000, v193
	v_pk_add_f32 v[154:155], v[154:155], 0 op_sel_hi:[1,0]
	v_pk_fma_f32 v[146:147], v[148:149], 0.5, v[146:147] op_sel_hi:[1,0,1]
	v_pk_add_f32 v[156:157], v[156:157], 0 op_sel_hi:[1,0]
	v_pk_add_f32 v[192:193], v[146:147], 0 op_sel_hi:[1,0]
	v_cvt_pk_bf16_f32 v146, v154, v155
	v_lshl_add_u64 v[154:155], s[88:89], 0, v[238:239]
	v_cvt_pk_bf16_f32 v147, v156, v157
	v_cvt_pk_bf16_f32 v148, v190, v191
	v_cvt_pk_bf16_f32 v149, v192, v193
	v_lshl_add_u64 v[154:155], v[154:155], 0, v[236:237]
	global_store_dwordx4 v[154:155], v[146:149], off
	v_lshlrev_b32_e32 v156, 16, v146
	v_lshlrev_b32_e32 v157, 16, v147
	v_and_b32_e32 v146, 0xffff0000, v146
	v_and_b32_e32 v147, 0xffff0000, v147
	v_mul_f32_e32 v146, v146, v146
	v_mul_f32_e32 v147, v147, v147
	v_lshlrev_b32_e32 v190, 16, v148
	v_and_b32_e32 v148, 0xffff0000, v148
	v_fmac_f32_e32 v146, v156, v156
	v_fmac_f32_e32 v147, v157, v157
	v_add_f32_e32 v146, v146, v147
	v_mul_f32_e32 v147, v148, v148
	v_lshlrev_b32_e32 v191, 16, v149
	v_and_b32_e32 v149, 0xffff0000, v149
	v_fmac_f32_e32 v147, v190, v190
	v_add_f32_e32 v146, v147, v146
	v_mul_f32_e32 v147, v149, v149
	v_fmac_f32_e32 v147, v191, v191
	v_add_f32_e32 v156, v147, v146
	s_waitcnt vmcnt(15)
	v_lshlrev_b32_e32 v146, 16, v186
	v_and_b32_e32 v147, 0xffff0000, v186
	v_pk_fma_f32 v[134:135], v[134:135], 0.5, v[146:147] op_sel_hi:[1,0,1]
	v_lshlrev_b32_e32 v146, 16, v187
	v_and_b32_e32 v147, 0xffff0000, v187
	v_pk_fma_f32 v[136:137], v[136:137], 0.5, v[146:147] op_sel_hi:[1,0,1]
	v_lshlrev_b32_e32 v146, 16, v188
	v_and_b32_e32 v147, 0xffff0000, v188
	v_pk_fma_f32 v[130:131], v[130:131], 0.5, v[146:147] op_sel_hi:[1,0,1]
	v_pk_add_f32 v[134:135], v[134:135], 0 op_sel_hi:[1,0]
	v_pk_add_f32 v[146:147], v[130:131], 0 op_sel_hi:[1,0]
	v_lshlrev_b32_e32 v130, 16, v189
	v_and_b32_e32 v131, 0xffff0000, v189
	v_pk_fma_f32 v[130:131], v[132:133], 0.5, v[130:131] op_sel_hi:[1,0,1]
	v_pk_add_f32 v[136:137], v[136:137], 0 op_sel_hi:[1,0]
	v_pk_add_f32 v[148:149], v[130:131], 0 op_sel_hi:[1,0]
	v_cvt_pk_bf16_f32 v130, v134, v135
	v_cvt_pk_bf16_f32 v131, v136, v137
	v_cvt_pk_bf16_f32 v132, v146, v147
	v_cvt_pk_bf16_f32 v133, v148, v149
	global_store_dwordx4 v[154:155], v[130:133], off offset:256
	v_lshlrev_b32_e32 v134, 16, v130
	v_lshlrev_b32_e32 v135, 16, v131
	v_and_b32_e32 v130, 0xffff0000, v130
	v_and_b32_e32 v131, 0xffff0000, v131
	v_mul_f32_e32 v130, v130, v130
	v_fmac_f32_e32 v130, v134, v134
	v_mul_f32_e32 v131, v131, v131
	v_lshlrev_b32_e32 v136, 16, v132
	v_and_b32_e32 v132, 0xffff0000, v132
	v_add_f32_e32 v130, v130, v156
	v_fmac_f32_e32 v131, v135, v135
	v_add_f32_e32 v130, v131, v130
	v_mul_f32_e32 v131, v132, v132
	v_lshlrev_b32_e32 v137, 16, v133
	v_and_b32_e32 v133, 0xffff0000, v133
	v_fmac_f32_e32 v131, v136, v136
	v_add_f32_e32 v130, v131, v130
	v_mul_f32_e32 v131, v133, v133
	v_fmac_f32_e32 v131, v137, v137
	v_add_f32_e32 v130, v131, v130
	v_mov_b32_e32 v131, v130
	s_nop 1
	v_permlane16_swap_b32_e32 v131, v130
	s_waitcnt lgkmcnt(0)
	v_add_f32_e32 v130, v130, v131
	v_mov_b32_e32 v131, v130
	s_nop 1
	v_permlane32_swap_b32_e32 v131, v130
	s_and_saveexec_b64 s[48:49], vcc
	s_mov_b32 s31, 0xf800000
	s_cbranch_execz .LBB0_276
	v_lshlrev_b64 v[132:133], 6, v[234:235]
	v_lshl_add_u64 v[132:133], s[38:39], 0, v[132:133]
	v_lshl_add_u64 v[132:133], s[82:83], 2, v[132:133]
	s_lshl_b32 s76, s55, 2
	v_lshl_add_u64 v[132:133], v[132:133], 0, s[76:77]
	s_waitcnt lgkmcnt(0)
	v_add_f32_e32 v130, v130, v131
	global_store_dword v[132:133], v130, off
